# phase 0 rmsnorm loop rewritten by hand as a two-deep software pipeline (next iteration's 8 loads in flight while the current two rows are reduced, scaled and stored)
# speedup vs baseline: 1.0091x; 1.0018x over previous
; __device__ void phase0(const Params& p, unsigned char* smem) {
;     ...
;     const int rstride = gridDim.x * 8;
;     for (int row = blockIdx.x * 8 + wave; row < NTOK; row += 2 * rstride) {
;       const int row2 = row + rstride;
;       const bool has2 = row2 < NTOK;
;       const float4* xr = (const float4*)xrow(p, row);
;       const float4* xr2 = (const float4*)xrow(p, has2 ? row2 : row);
;       float4 v[4], w[4];
;       float ss = 0.f, ss2 = 0.f;
; #pragma unroll
;       for (int i = 0; i < 4; i++) { v[i] = xr[lane + 64 * i]; w[i] = xr2[lane + 64 * i]; }
.LBB0_163:
	s_or_b64 exec, exec, s[60:61]
	global_load_ushort v2, v[40:41], off offset:18
	s_mov_b32 s0, 0x8200
	v_and_b32_e32 v36, 0x3ff, v0
	s_waitcnt vmcnt(0)
	v_cmp_ne_u16_e32 vcc, 0, v2
	s_nop 1
	v_addc_co_u32_e32 v38, vcc, 0, v1, vcc
	v_cmp_gt_i32_e32 vcc, s0, v34
	s_and_saveexec_b64 s[10:11], vcc
	s_cbranch_execz .LBB0_174
	s_load_dwordx4 s[16:19], s[92:93], 0x0
	s_load_dwordx2 s[20:21], s[92:93], 0x38
	v_and_b32_e32 v2, 63, v0
	v_lshlrev_b32_e32 v3, 4, v2
	v_lshlrev_b32_e32 v4, 3, v2
	v_mov_b32_e32 v5, 0x358637bd
	v_readfirstlane_b32 s22, v34
	s_add_u32 s24, s88, 0x2020800
	s_addc_u32 s25, s89, 0
	s_mov_b32 s23, 0x800000
	s_mov_b32 s26, 1
	s_waitcnt lgkmcnt(0)
	global_load_dwordx4 v[8:11], v3, s[20:21]
	global_load_dwordx4 v[12:15], v3, s[20:21] offset:1024
	global_load_dwordx4 v[16:19], v3, s[20:21] offset:2048
	global_load_dwordx4 v[20:23], v3, s[20:21] offset:3072
	s_waitcnt vmcnt(0)
	s_add_i32 s29, s22, 0x800
	s_cmp_lt_u32 s29, 0x8200
	s_cselect_b32 s29, s29, s22
	s_cmp_lt_u32 s22, 0x8000
	s_cselect_b32 s30, s16, s18
	s_cselect_b32 s31, s17, s19
	s_cselect_b32 s34, 0, 0x8000
	s_sub_u32 s34, s22, s34
	s_mov_b32 s35, 0
	s_lshl_b64 s[34:35], s[34:35], 12
	s_add_u32 s30, s30, s34
	s_addc_u32 s31, s31, s35
	s_cmp_lt_u32 s29, 0x8000
	s_cselect_b32 s32, s16, s18
	s_cselect_b32 s33, s17, s19
	s_cselect_b32 s34, 0, 0x8000
	s_sub_u32 s34, s29, s34
	s_mov_b32 s35, 0
	s_lshl_b64 s[34:35], s[34:35], 12
	s_add_u32 s32, s32, s34
	s_addc_u32 s33, s33, s35
	global_load_dwordx4 v[64:67], v3, s[30:31]
	global_load_dwordx4 v[68:71], v3, s[30:31] offset:1024
	global_load_dwordx4 v[72:75], v3, s[30:31] offset:2048
	global_load_dwordx4 v[76:79], v3, s[30:31] offset:3072
	global_load_dwordx4 v[80:83], v3, s[32:33]
	global_load_dwordx4 v[84:87], v3, s[32:33] offset:1024
	global_load_dwordx4 v[88:91], v3, s[32:33] offset:2048
	global_load_dwordx4 v[92:95], v3, s[32:33] offset:3072
.Lxn_loop:
	s_add_i32 s27, s22, 0x1000
	s_cmp_lt_u32 s27, 0x8200
	s_cselect_b32 s28, 1, 0
	s_cbranch_scc0 .Lxn_nonext_a
	s_add_i32 s29, s27, 0x800
	s_cmp_lt_u32 s29, 0x8200
	s_cselect_b32 s29, s29, s27
	s_cmp_lt_u32 s27, 0x8000
	s_cselect_b32 s30, s16, s18
	s_cselect_b32 s31, s17, s19
	s_cselect_b32 s34, 0, 0x8000
	s_sub_u32 s34, s27, s34
	s_mov_b32 s35, 0
	s_lshl_b64 s[34:35], s[34:35], 12
	s_add_u32 s30, s30, s34
	s_addc_u32 s31, s31, s35
	s_cmp_lt_u32 s29, 0x8000
	s_cselect_b32 s32, s16, s18
	s_cselect_b32 s33, s17, s19
	s_cselect_b32 s34, 0, 0x8000
	s_sub_u32 s34, s29, s34
	s_mov_b32 s35, 0
	s_lshl_b64 s[34:35], s[34:35], 12
	s_add_u32 s32, s32, s34
	s_addc_u32 s33, s33, s35
	global_load_dwordx4 v[96:99], v3, s[30:31]
	global_load_dwordx4 v[100:103], v3, s[30:31] offset:1024
	global_load_dwordx4 v[104:107], v3, s[30:31] offset:2048
	global_load_dwordx4 v[108:111], v3, s[30:31] offset:3072
	global_load_dwordx4 v[112:115], v3, s[32:33]
	global_load_dwordx4 v[116:119], v3, s[32:33] offset:1024
	global_load_dwordx4 v[120:123], v3, s[32:33] offset:2048
	global_load_dwordx4 v[124:127], v3, s[32:33] offset:3072
	s_cmp_lg_u32 s26, 0
	s_cbranch_scc1 .Lxn_w8_a
	s_waitcnt vmcnt(16)
	s_branch .Lxn_go_a
.Lxn_nonext_a:
	s_cmp_lg_u32 s26, 0
	s_cbranch_scc1 .Lxn_w0_a
.Lxn_w8_a:
	s_waitcnt vmcnt(8)
	s_branch .Lxn_go_a

; __device__ void phase0(const Params& p, unsigned char* smem) {
;     ...
;       for (int i = 0; i < 4; i++) {
;         ss += v[i].x * v[i].x + v[i].y * v[i].y + v[i].z * v[i].z + v[i].w * v[i].w;
;         ss2 += w[i].x * w[i].x + w[i].y * w[i].y + w[i].z * w[i].z + w[i].w * w[i].w;
;       }
; #pragma unroll
;       for (int o = 32; o >= 1; o >>= 1) { ss += __shfl_xor(ss, o); ss2 += __shfl_xor(ss2, o); }
;       const float rs = rsqrtf(ss * (1.f / 1024.f) + 1e-6f), rs2 = rsqrtf(ss2 * (1.f / 1024.f) + 1e-6f);
; #pragma unroll
;       for (int i = 0; i < 4; i++) {
;         const float4 gg = ((const float4*)g)[lane + 64 * i];
;         uint2 o;
;         o.x = pack2(v[i].x * rs * gg.x, v[i].y * rs * gg.y);
;         o.y = pack2(v[i].z * rs * gg.z, v[i].w * rs * gg.w);
;         *(uint2*)(XN + (size_t)row * 1024 + (lane + 64 * i) * 4) = o;
;         if (has2) {
;           uint2 o2;
;           o2.x = pack2(w[i].x * rs2 * gg.x, w[i].y * rs2 * gg.y);
;           o2.y = pack2(w[i].z * rs2 * gg.z, w[i].w * rs2 * gg.w);
;           *(uint2*)(XN + (size_t)row2 * 1024 + (lane + 64 * i) * 4) = o2;
;         }
;       }
.Lxn_go_a:
	v_mul_f32_e32 v24, v64, v64
	v_mul_f32_e32 v25, v80, v80
	v_fmac_f32_e32 v24, v65, v65
	v_fmac_f32_e32 v25, v81, v81
	v_fmac_f32_e32 v24, v66, v66
	v_fmac_f32_e32 v25, v82, v82
	v_fmac_f32_e32 v24, v67, v67
	v_fmac_f32_e32 v25, v83, v83
	v_fmac_f32_e32 v24, v68, v68
	v_fmac_f32_e32 v25, v84, v84
	v_fmac_f32_e32 v24, v69, v69
	v_fmac_f32_e32 v25, v85, v85
	v_fmac_f32_e32 v24, v70, v70
	v_fmac_f32_e32 v25, v86, v86
	v_fmac_f32_e32 v24, v71, v71
	v_fmac_f32_e32 v25, v87, v87
	v_fmac_f32_e32 v24, v72, v72
	v_fmac_f32_e32 v25, v88, v88
	v_fmac_f32_e32 v24, v73, v73
	v_fmac_f32_e32 v25, v89, v89
	v_fmac_f32_e32 v24, v74, v74
	v_fmac_f32_e32 v25, v90, v90
	v_fmac_f32_e32 v24, v75, v75
	v_fmac_f32_e32 v25, v91, v91
	v_fmac_f32_e32 v24, v76, v76
	v_fmac_f32_e32 v25, v92, v92
	v_fmac_f32_e32 v24, v77, v77
	v_fmac_f32_e32 v25, v93, v93
	v_fmac_f32_e32 v24, v78, v78
	v_fmac_f32_e32 v25, v94, v94
	v_fmac_f32_e32 v24, v79, v79
	v_fmac_f32_e32 v25, v95, v95
	s_nop 1
	v_add_f32_dpp v24, v24, v24 quad_perm:[1,0,3,2] row_mask:0xf bank_mask:0xf
	v_add_f32_dpp v25, v25, v25 quad_perm:[1,0,3,2] row_mask:0xf bank_mask:0xf
	s_nop 1
	v_add_f32_dpp v24, v24, v24 quad_perm:[2,3,0,1] row_mask:0xf bank_mask:0xf
	v_add_f32_dpp v25, v25, v25 quad_perm:[2,3,0,1] row_mask:0xf bank_mask:0xf
	s_nop 1
	v_add_f32_dpp v24, v24, v24 row_half_mirror row_mask:0xf bank_mask:0xf
	v_add_f32_dpp v25, v25, v25 row_half_mirror row_mask:0xf bank_mask:0xf
	s_nop 1
	v_add_f32_dpp v24, v24, v24 row_mirror row_mask:0xf bank_mask:0xf
	v_add_f32_dpp v25, v25, v25 row_mirror row_mask:0xf bank_mask:0xf
	v_mov_b32_e32 v26, v24
	v_mov_b32_e32 v27, v25
	s_nop 1
	v_permlane16_swap_b32_e32 v24, v26
	v_permlane16_swap_b32_e32 v25, v27
	v_add_f32_e32 v24, v24, v26
	v_add_f32_e32 v25, v25, v27
	v_mov_b32_e32 v26, v24
	v_mov_b32_e32 v27, v25
	s_nop 1
	v_permlane32_swap_b32_e32 v24, v26
	v_permlane32_swap_b32_e32 v25, v27
	v_add_f32_e32 v24, v24, v26
	v_add_f32_e32 v25, v25, v27
	v_fmamk_f32 v28, v24, 0x3a800000, v5
	v_mul_f32_e32 v32, 0x4b800000, v28
	v_cmp_gt_f32_e32 vcc, s23, v28
	s_nop 1
	v_cndmask_b32_e32 v28, v28, v32, vcc
	v_rsq_f32_e32 v28, v28
	s_nop 0
	v_mul_f32_e32 v32, 0x45800000, v28
	v_cndmask_b32_e32 v28, v28, v32, vcc
	v_fmamk_f32 v30, v25, 0x3a800000, v5
	v_mul_f32_e32 v33, 0x4b800000, v30
	v_cmp_gt_f32_e32 vcc, s23, v30
	s_nop 1
	v_cndmask_b32_e32 v30, v30, v33, vcc
	v_rsq_f32_e32 v30, v30
	s_nop 0
	v_mul_f32_e32 v33, 0x45800000, v30
	v_cndmask_b32_e32 v30, v30, v33, vcc
	s_lshl_b32 s36, s22, 11
	s_lshr_b32 s37, s22, 21
	s_add_u32 s36, s24, s36
	s_addc_u32 s37, s25, s37
	v_pk_mul_f32 v[64:65], v[64:65], v[28:29] op_sel_hi:[1,0]
	v_pk_mul_f32 v[66:67], v[66:67], v[28:29] op_sel_hi:[1,0]
	v_pk_mul_f32 v[68:69], v[68:69], v[28:29] op_sel_hi:[1,0]
	v_pk_mul_f32 v[70:71], v[70:71], v[28:29] op_sel_hi:[1,0]
	v_pk_mul_f32 v[72:73], v[72:73], v[28:29] op_sel_hi:[1,0]
	v_pk_mul_f32 v[74:75], v[74:75], v[28:29] op_sel_hi:[1,0]
	v_pk_mul_f32 v[76:77], v[76:77], v[28:29] op_sel_hi:[1,0]
	v_pk_mul_f32 v[78:79], v[78:79], v[28:29] op_sel_hi:[1,0]
	v_pk_mul_f32 v[64:65], v[64:65], v[8:9]
	v_pk_mul_f32 v[66:67], v[66:67], v[10:11]
	v_pk_mul_f32 v[68:69], v[68:69], v[12:13]
	v_pk_mul_f32 v[70:71], v[70:71], v[14:15]
	v_pk_mul_f32 v[72:73], v[72:73], v[16:17]
	v_pk_mul_f32 v[74:75], v[74:75], v[18:19]
	v_pk_mul_f32 v[76:77], v[76:77], v[20:21]
	v_pk_mul_f32 v[78:79], v[78:79], v[22:23]
	v_cvt_pk_bf16_f32 v128, v64, v65
	v_cvt_pk_bf16_f32 v129, v66, v67
	v_cvt_pk_bf16_f32 v130, v68, v69
	v_cvt_pk_bf16_f32 v131, v70, v71
	v_cvt_pk_bf16_f32 v132, v72, v73
	v_cvt_pk_bf16_f32 v133, v74, v75
	v_cvt_pk_bf16_f32 v134, v76, v77
	v_cvt_pk_bf16_f32 v135, v78, v79
	global_store_dwordx2 v4, v[128:129], s[36:37]
	global_store_dwordx2 v4, v[130:131], s[36:37] offset:512
	global_store_dwordx2 v4, v[132:133], s[36:37] offset:1024
	global_store_dwordx2 v4, v[134:135], s[36:37] offset:1536
	s_add_i32 s29, s22, 0x800
	s_cmp_lt_u32 s29, 0x8200
	s_cbranch_scc0 .Lxn_no2_a
	s_add_u32 s36, s36, 0x400000
	s_addc_u32 s37, s37, 0
	v_pk_mul_f32 v[80:81], v[80:81], v[30:31] op_sel_hi:[1,0]
	v_pk_mul_f32 v[82:83], v[82:83], v[30:31] op_sel_hi:[1,0]
	v_pk_mul_f32 v[84:85], v[84:85], v[30:31] op_sel_hi:[1,0]
	v_pk_mul_f32 v[86:87], v[86:87], v[30:31] op_sel_hi:[1,0]
	v_pk_mul_f32 v[88:89], v[88:89], v[30:31] op_sel_hi:[1,0]
	v_pk_mul_f32 v[90:91], v[90:91], v[30:31] op_sel_hi:[1,0]
	v_pk_mul_f32 v[92:93], v[92:93], v[30:31] op_sel_hi:[1,0]
	v_pk_mul_f32 v[94:95], v[94:95], v[30:31] op_sel_hi:[1,0]
	v_pk_mul_f32 v[80:81], v[80:81], v[8:9]
	v_pk_mul_f32 v[82:83], v[82:83], v[10:11]
	v_pk_mul_f32 v[84:85], v[84:85], v[12:13]
	v_pk_mul_f32 v[86:87], v[86:87], v[14:15]
	v_pk_mul_f32 v[88:89], v[88:89], v[16:17]
	v_pk_mul_f32 v[90:91], v[90:91], v[18:19]
	v_pk_mul_f32 v[92:93], v[92:93], v[20:21]
	v_pk_mul_f32 v[94:95], v[94:95], v[22:23]
	v_cvt_pk_bf16_f32 v136, v80, v81
	v_cvt_pk_bf16_f32 v137, v82, v83
	v_cvt_pk_bf16_f32 v138, v84, v85
	v_cvt_pk_bf16_f32 v139, v86, v87
	v_cvt_pk_bf16_f32 v140, v88, v89
	v_cvt_pk_bf16_f32 v141, v90, v91
	v_cvt_pk_bf16_f32 v142, v92, v93
	v_cvt_pk_bf16_f32 v143, v94, v95
	global_store_dwordx2 v4, v[136:137], s[36:37]
	global_store_dwordx2 v4, v[138:139], s[36:37] offset:512
	global_store_dwordx2 v4, v[140:141], s[36:37] offset:1024
	global_store_dwordx2 v4, v[142:143], s[36:37] offset:1536
.Lxn_no2_a:
	s_mov_b32 s26, 0
	s_mov_b32 s22, s27
	s_cmp_lg_u32 s28, 0
	s_cbranch_scc0 .Lxn_done
	s_add_i32 s27, s22, 0x1000
	s_cmp_lt_u32 s27, 0x8200
	s_cselect_b32 s28, 1, 0
	s_cbranch_scc0 .Lxn_nonext_b
	s_add_i32 s29, s27, 0x800
	s_cmp_lt_u32 s29, 0x8200
	s_cselect_b32 s29, s29, s27
	s_cmp_lt_u32 s27, 0x8000
	s_cselect_b32 s30, s16, s18
	s_cselect_b32 s31, s17, s19
	s_cselect_b32 s34, 0, 0x8000
	s_sub_u32 s34, s27, s34
	s_mov_b32 s35, 0
	s_lshl_b64 s[34:35], s[34:35], 12
	s_add_u32 s30, s30, s34
	s_addc_u32 s31, s31, s35
	s_cmp_lt_u32 s29, 0x8000
	s_cselect_b32 s32, s16, s18
	s_cselect_b32 s33, s17, s19
	s_cselect_b32 s34, 0, 0x8000
	s_sub_u32 s34, s29, s34
	s_mov_b32 s35, 0
	s_lshl_b64 s[34:35], s[34:35], 12
	s_add_u32 s32, s32, s34
	s_addc_u32 s33, s33, s35
	global_load_dwordx4 v[64:67], v3, s[30:31]
	global_load_dwordx4 v[68:71], v3, s[30:31] offset:1024
	global_load_dwordx4 v[72:75], v3, s[30:31] offset:2048
	global_load_dwordx4 v[76:79], v3, s[30:31] offset:3072
	global_load_dwordx4 v[80:83], v3, s[32:33]
	global_load_dwordx4 v[84:87], v3, s[32:33] offset:1024
	global_load_dwordx4 v[88:91], v3, s[32:33] offset:2048
	global_load_dwordx4 v[92:95], v3, s[32:33] offset:3072
	s_cmp_lg_u32 s26, 0
	s_cbranch_scc1 .Lxn_w8_b
	s_waitcnt vmcnt(16)
	s_branch .Lxn_go_b

; __device__ void phase0(const Params& p, unsigned char* smem) {
;     ...
;     for (int row = blockIdx.x * 8 + wave; row < NTOK; row += 2 * rstride) {
;       const int row2 = row + rstride;
;       const bool has2 = row2 < NTOK;
;       const float4* xr = (const float4*)xrow(p, row);
;       const float4* xr2 = (const float4*)xrow(p, has2 ? row2 : row);
;       float4 v[4], w[4];
;       float ss = 0.f, ss2 = 0.f;
; #pragma unroll
;       for (int i = 0; i < 4; i++) { v[i] = xr[lane + 64 * i]; w[i] = xr2[lane + 64 * i]; }
; #pragma unroll
;       for (int i = 0; i < 4; i++) {
;         ss += v[i].x * v[i].x + v[i].y * v[i].y + v[i].z * v[i].z + v[i].w * v[i].w;
;         ss2 += w[i].x * w[i].x + w[i].y * w[i].y + w[i].z * w[i].z + w[i].w * w[i].w;
;       }
; #pragma unroll
;       for (int o = 32; o >= 1; o >>= 1) { ss += __shfl_xor(ss, o); ss2 += __shfl_xor(ss2, o); }
;       const float rs = rsqrtf(ss * (1.f / 1024.f) + 1e-6f), rs2 = rsqrtf(ss2 * (1.f / 1024.f) + 1e-6f);
; #pragma unroll
;       for (int i = 0; i < 4; i++) {
;         const float4 gg = ((const float4*)g)[lane + 64 * i];
;         uint2 o;
;         o.x = pack2(v[i].x * rs * gg.x, v[i].y * rs * gg.y);
;         o.y = pack2(v[i].z * rs * gg.z, v[i].w * rs * gg.w);
;         *(uint2*)(XN + (size_t)row * 1024 + (lane + 64 * i) * 4) = o;
;         if (has2) {
;           uint2 o2;
;           o2.x = pack2(w[i].x * rs2 * gg.x, w[i].y * rs2 * gg.y);
;           o2.y = pack2(w[i].z * rs2 * gg.z, w[i].w * rs2 * gg.w);
;           *(uint2*)(XN + (size_t)row2 * 1024 + (lane + 64 * i) * 4) = o2;
;         }
;       }
;     }
.Lxn_go_b:
	v_mul_f32_e32 v24, v96, v96
	v_mul_f32_e32 v25, v112, v112
	v_fmac_f32_e32 v24, v97, v97
	v_fmac_f32_e32 v25, v113, v113
	v_fmac_f32_e32 v24, v98, v98
	v_fmac_f32_e32 v25, v114, v114
	v_fmac_f32_e32 v24, v99, v99
	v_fmac_f32_e32 v25, v115, v115
	v_fmac_f32_e32 v24, v100, v100
	v_fmac_f32_e32 v25, v116, v116
	v_fmac_f32_e32 v24, v101, v101
	v_fmac_f32_e32 v25, v117, v117
	v_fmac_f32_e32 v24, v102, v102
	v_fmac_f32_e32 v25, v118, v118
	v_fmac_f32_e32 v24, v103, v103
	v_fmac_f32_e32 v25, v119, v119
	v_fmac_f32_e32 v24, v104, v104
	v_fmac_f32_e32 v25, v120, v120
	v_fmac_f32_e32 v24, v105, v105
	v_fmac_f32_e32 v25, v121, v121
	v_fmac_f32_e32 v24, v106, v106
	v_fmac_f32_e32 v25, v122, v122
	v_fmac_f32_e32 v24, v107, v107
	v_fmac_f32_e32 v25, v123, v123
	v_fmac_f32_e32 v24, v108, v108
	v_fmac_f32_e32 v25, v124, v124
	v_fmac_f32_e32 v24, v109, v109
	v_fmac_f32_e32 v25, v125, v125
	v_fmac_f32_e32 v24, v110, v110
	v_fmac_f32_e32 v25, v126, v126
	v_fmac_f32_e32 v24, v111, v111
	v_fmac_f32_e32 v25, v127, v127
	s_nop 1
	v_add_f32_dpp v24, v24, v24 quad_perm:[1,0,3,2] row_mask:0xf bank_mask:0xf
	v_add_f32_dpp v25, v25, v25 quad_perm:[1,0,3,2] row_mask:0xf bank_mask:0xf
	s_nop 1
	v_add_f32_dpp v24, v24, v24 quad_perm:[2,3,0,1] row_mask:0xf bank_mask:0xf
	v_add_f32_dpp v25, v25, v25 quad_perm:[2,3,0,1] row_mask:0xf bank_mask:0xf
	s_nop 1
	v_add_f32_dpp v24, v24, v24 row_half_mirror row_mask:0xf bank_mask:0xf
	v_add_f32_dpp v25, v25, v25 row_half_mirror row_mask:0xf bank_mask:0xf
	s_nop 1
	v_add_f32_dpp v24, v24, v24 row_mirror row_mask:0xf bank_mask:0xf
	v_add_f32_dpp v25, v25, v25 row_mirror row_mask:0xf bank_mask:0xf
	v_mov_b32_e32 v26, v24
	v_mov_b32_e32 v27, v25
	s_nop 1
	v_permlane16_swap_b32_e32 v24, v26
	v_permlane16_swap_b32_e32 v25, v27
	v_add_f32_e32 v24, v24, v26
	v_add_f32_e32 v25, v25, v27
	v_mov_b32_e32 v26, v24
	v_mov_b32_e32 v27, v25
	s_nop 1
	v_permlane32_swap_b32_e32 v24, v26
	v_permlane32_swap_b32_e32 v25, v27
	v_add_f32_e32 v24, v24, v26
	v_add_f32_e32 v25, v25, v27
	v_fmamk_f32 v28, v24, 0x3a800000, v5
	v_mul_f32_e32 v32, 0x4b800000, v28
	v_cmp_gt_f32_e32 vcc, s23, v28
	s_nop 1
	v_cndmask_b32_e32 v28, v28, v32, vcc
	v_rsq_f32_e32 v28, v28
	s_nop 0
	v_mul_f32_e32 v32, 0x45800000, v28
	v_cndmask_b32_e32 v28, v28, v32, vcc
	v_fmamk_f32 v30, v25, 0x3a800000, v5
	v_mul_f32_e32 v33, 0x4b800000, v30
	v_cmp_gt_f32_e32 vcc, s23, v30
	s_nop 1
	v_cndmask_b32_e32 v30, v30, v33, vcc
	v_rsq_f32_e32 v30, v30
	s_nop 0
	v_mul_f32_e32 v33, 0x45800000, v30
	v_cndmask_b32_e32 v30, v30, v33, vcc
	s_lshl_b32 s36, s22, 11
	s_lshr_b32 s37, s22, 21
	s_add_u32 s36, s24, s36
	s_addc_u32 s37, s25, s37
	v_pk_mul_f32 v[96:97], v[96:97], v[28:29] op_sel_hi:[1,0]
	v_pk_mul_f32 v[98:99], v[98:99], v[28:29] op_sel_hi:[1,0]
	v_pk_mul_f32 v[100:101], v[100:101], v[28:29] op_sel_hi:[1,0]
	v_pk_mul_f32 v[102:103], v[102:103], v[28:29] op_sel_hi:[1,0]
	v_pk_mul_f32 v[104:105], v[104:105], v[28:29] op_sel_hi:[1,0]
	v_pk_mul_f32 v[106:107], v[106:107], v[28:29] op_sel_hi:[1,0]
	v_pk_mul_f32 v[108:109], v[108:109], v[28:29] op_sel_hi:[1,0]
	v_pk_mul_f32 v[110:111], v[110:111], v[28:29] op_sel_hi:[1,0]
	v_pk_mul_f32 v[96:97], v[96:97], v[8:9]
	v_pk_mul_f32 v[98:99], v[98:99], v[10:11]
	v_pk_mul_f32 v[100:101], v[100:101], v[12:13]
	v_pk_mul_f32 v[102:103], v[102:103], v[14:15]
	v_pk_mul_f32 v[104:105], v[104:105], v[16:17]
	v_pk_mul_f32 v[106:107], v[106:107], v[18:19]
	v_pk_mul_f32 v[108:109], v[108:109], v[20:21]
	v_pk_mul_f32 v[110:111], v[110:111], v[22:23]
	v_cvt_pk_bf16_f32 v128, v96, v97
	v_cvt_pk_bf16_f32 v129, v98, v99
	v_cvt_pk_bf16_f32 v130, v100, v101
	v_cvt_pk_bf16_f32 v131, v102, v103
	v_cvt_pk_bf16_f32 v132, v104, v105
	v_cvt_pk_bf16_f32 v133, v106, v107
	v_cvt_pk_bf16_f32 v134, v108, v109
	v_cvt_pk_bf16_f32 v135, v110, v111
	global_store_dwordx2 v4, v[128:129], s[36:37]
	global_store_dwordx2 v4, v[130:131], s[36:37] offset:512
	global_store_dwordx2 v4, v[132:133], s[36:37] offset:1024
	global_store_dwordx2 v4, v[134:135], s[36:37] offset:1536
	s_add_i32 s29, s22, 0x800
	s_cmp_lt_u32 s29, 0x8200
	s_cbranch_scc0 .Lxn_no2_b
	s_add_u32 s36, s36, 0x400000
	s_addc_u32 s37, s37, 0
	v_pk_mul_f32 v[112:113], v[112:113], v[30:31] op_sel_hi:[1,0]
	v_pk_mul_f32 v[114:115], v[114:115], v[30:31] op_sel_hi:[1,0]
	v_pk_mul_f32 v[116:117], v[116:117], v[30:31] op_sel_hi:[1,0]
	v_pk_mul_f32 v[118:119], v[118:119], v[30:31] op_sel_hi:[1,0]
	v_pk_mul_f32 v[120:121], v[120:121], v[30:31] op_sel_hi:[1,0]
	v_pk_mul_f32 v[122:123], v[122:123], v[30:31] op_sel_hi:[1,0]
	v_pk_mul_f32 v[124:125], v[124:125], v[30:31] op_sel_hi:[1,0]
	v_pk_mul_f32 v[126:127], v[126:127], v[30:31] op_sel_hi:[1,0]
	v_pk_mul_f32 v[112:113], v[112:113], v[8:9]
	v_pk_mul_f32 v[114:115], v[114:115], v[10:11]
	v_pk_mul_f32 v[116:117], v[116:117], v[12:13]
	v_pk_mul_f32 v[118:119], v[118:119], v[14:15]
	v_pk_mul_f32 v[120:121], v[120:121], v[16:17]
	v_pk_mul_f32 v[122:123], v[122:123], v[18:19]
	v_pk_mul_f32 v[124:125], v[124:125], v[20:21]
	v_pk_mul_f32 v[126:127], v[126:127], v[22:23]
	v_cvt_pk_bf16_f32 v136, v112, v113
	v_cvt_pk_bf16_f32 v137, v114, v115
	v_cvt_pk_bf16_f32 v138, v116, v117
	v_cvt_pk_bf16_f32 v139, v118, v119
	v_cvt_pk_bf16_f32 v140, v120, v121
	v_cvt_pk_bf16_f32 v141, v122, v123
	v_cvt_pk_bf16_f32 v142, v124, v125
	v_cvt_pk_bf16_f32 v143, v126, v127
	global_store_dwordx2 v4, v[136:137], s[36:37]
	global_store_dwordx2 v4, v[138:139], s[36:37] offset:512
	global_store_dwordx2 v4, v[140:141], s[36:37] offset:1024
	global_store_dwordx2 v4, v[142:143], s[36:37] offset:1536
; __device__ void phase0(const Params& p, unsigned char* smem) {
;     ...
;     for (int row = blockIdx.x * 8 + wave; row < NTOK; row += 2 * rstride) {
;       const int row2 = row + rstride;
;       const bool has2 = row2 < NTOK;
;       const float4* xr = (const float4*)xrow(p, row);
;       const float4* xr2 = (const float4*)xrow(p, has2 ? row2 : row);
;       float4 v[4], w[4];
;       float ss = 0.f, ss2 = 0.f;
; #pragma unroll
;       for (int i = 0; i < 4; i++) { v[i] = xr[lane + 64 * i]; w[i] = xr2[lane + 64 * i]; }
; #pragma unroll
;       for (int i = 0; i < 4; i++) {
;         ss += v[i].x * v[i].x + v[i].y * v[i].y + v[i].z * v[i].z + v[i].w * v[i].w;
;         ss2 += w[i].x * w[i].x + w[i].y * w[i].y + w[i].z * w[i].z + w[i].w * w[i].w;
;       }
; #pragma unroll
;       for (int o = 32; o >= 1; o >>= 1) { ss += __shfl_xor(ss, o); ss2 += __shfl_xor(ss2, o); }
;       const float rs = rsqrtf(ss * (1.f / 1024.f) + 1e-6f), rs2 = rsqrtf(ss2 * (1.f / 1024.f) + 1e-6f);
; #pragma unroll
;       for (int i = 0; i < 4; i++) {
;         const float4 gg = ((const float4*)g)[lane + 64 * i];
;         uint2 o;
;         o.x = pack2(v[i].x * rs * gg.x, v[i].y * rs * gg.y);
;         o.y = pack2(v[i].z * rs * gg.z, v[i].w * rs * gg.w);
;         *(uint2*)(XN + (size_t)row * 1024 + (lane + 64 * i) * 4) = o;
;         if (has2) {
;           uint2 o2;
;           o2.x = pack2(w[i].x * rs2 * gg.x, w[i].y * rs2 * gg.y);
;           o2.y = pack2(w[i].z * rs2 * gg.z, w[i].w * rs2 * gg.w);
;           *(uint2*)(XN + (size_t)row2 * 1024 + (lane + 64 * i) * 4) = o2;
;         }
;       }
;     }
;     ...
;   const size_t gtid = (size_t)blockIdx.x * blockDim.x + tid;
;   const size_t gsz = (size_t)gridDim.x * blockDim.x;
;   {
;     float2* CS = (float2*)(ws + OFF_CS);
;     for (size_t i = gtid; i < 8192 * 8; i += gsz) {
;       int pos = (int)(i >> 3), f = (int)(i & 7);
;       float inv = powf(500000.0f, -(float)f / 8.0f);
;       float ang = (float)pos * inv;
;       double rr = (double)ang;
;       rr = rr - 6.283185307179586 * rint(rr * 0.15915494309189535);
;       float s, c;
;       sincosf((float)rr, &s, &c);
;       CS[i] = make_float2(c, s);
;     }
.Lxn_no2_b:
	s_mov_b32 s26, 0
	s_mov_b32 s22, s27
	s_cmp_lg_u32 s28, 0
	s_cbranch_scc0 .Lxn_done
	s_branch .Lxn_loop
.Lxn_done:
.LBB0_174:
	s_or_b64 exec, exec, s[10:11]
	v_cmp_lt_u32_e32 vcc, s94, v1
	v_mov_b32_e32 v7, 0
	v_mov_b32_e32 v37, v7
	v_cndmask_b32_e64 v6, 18, 12, vcc
	v_lshl_add_u64 v[2:3], v[40:41], 0, v[6:7]
	global_load_ushort v1, v[2:3], off
	s_mov_b32 s95, 0
	s_waitcnt vmcnt(0)
	v_and_b32_e32 v42, 0xffff, v1
	v_mad_u64_u32 v[4:5], s[0:1], v42, s94, v[36:37]
	v_mad_u64_u32 v[2:3], s[0:1], v42, v38, 0
	s_mov_b64 s[0:1], 0x10000
	s_nop 0
	v_cmp_gt_u64_e32 vcc, s[0:1], v[4:5]
	s_and_saveexec_b64 s[10:11], vcc
	s_cbranch_execz .LBB0_181
	v_lshl_add_u64 v[8:9], v[4:5], 3, s[88:89]
	s_mov_b64 s[0:1], 0x1f80000
	s_mov_b32 s14, 0x6dc9c883
	s_mov_b32 s16, 0x54442d18
	v_lshl_add_u64 v[8:9], v[8:9], 0, s[0:1]
	v_lshlrev_b64 v[10:11], 3, v[2:3]
	s_mov_b64 s[12:13], 0
	v_mov_b32_e32 v14, 0x48f42400
	s_mov_b32 s0, 0x3f2aaaab
	v_mov_b32_e32 v15, 0x3e91f4c4
	s_mov_b32 s1, 0x3f317218
	s_movk_i32 s22, 0x204
	s_mov_b32 s23, 0x7f800000
	s_mov_b32 s24, 0x42b17218
	v_mov_b32_e32 v16, 0x37000000
	s_mov_b32 s25, 0x3fb8aa3b
	s_mov_b32 s26, 0xc2ce8ed0
	v_mov_b32_e32 v17, 0x7f800000
	s_mov_b32 s15, 0x3fc45f30
	s_mov_b32 s17, 0xc01921fb
	s_brev_b32 s27, 18
	s_mov_b32 s28, 0xfe5163ab
	s_mov_b32 s29, 0x3c439041
	s_mov_b32 s30, 0xdb629599
	s_mov_b32 s31, 0xf534ddc0
	s_mov_b32 s33, 0xfc2757d1
	s_mov_b32 s34, 0x4e441529
	s_mov_b32 s35, 0xa2f9836e
	s_mov_b32 s36, 0x3fc90fda
	s_mov_b32 s37, 0x3f22f983
	s_mov_b32 s38, 0xbfc90fda
	v_mov_b32_e32 v18, 0x3c0881c4
	v_mov_b32_e32 v19, 0xbab64f3b
	s_brev_b32 s39, 1
	s_movk_i32 s40, 0x1f8
	v_mov_b32_e32 v20, 0x7fc00000
	s_mov_b64 s[18:19], 0xffff
	v_not_b32_e32 v21, 63
	v_not_b32_e32 v22, 31
	v_mov_b64_e32 v[12:13], v[4:5]
	s_branch .LBB0_177
